# diff unit setup: wait for tile t0+1 moved from the setup start to its closing barrier (on top of the NA-end wait removal)
# speedup vs baseline: 1.0074x; 1.0074x over previous
.LBB0_574:
	s_add_i32 s11, s11, s17
	v_lshlrev_b32_e32 v182, 2, v0
	v_lshrrev_b32_e32 v3, 2, v1
	s_mul_hi_u32 s13, s11, 0x1200
	s_mulk_i32 s11, 0x1200
	v_readlane_b32 s16, v252, 52
	v_and_or_b32 v3, v3, 3, v182
	v_readlane_b32 s17, v252, 53
	s_add_u32 s12, s16, s11
	v_lshlrev_b32_e32 v4, 1, v1
	v_lshlrev_b32_e32 v184, 6, v3
	s_addc_u32 s13, s17, s13
	v_add_u32_e32 v3, 0x4000, v183
	v_and_b32_e32 v185, 32, v4
	v_lshl_add_u64 v[4:5], v[126:127], 1, s[12:13]
	s_mov_b64 s[16:17], 0xe00
	v_readfirstlane_b32 s11, v3
	v_add_u32_e32 v3, 0x6000, v183
	v_lshl_add_u64 v[4:5], v[4:5], 0, s[16:17]
	s_mov_b32 m0, s11
	v_readfirstlane_b32 s11, v3
	global_load_lds_dwordx4 v[4:5], off
	v_lshl_add_u64 v[4:5], v[124:125], 1, s[12:13]
	s_mov_b32 m0, s11
	v_lshlrev_b32_e32 v186, 7, v2
	global_load_lds_dwordx4 v[4:5], off
	v_lshrrev_b32_e32 v2, 1, v1
	v_bfe_u32 v1, v1, 1, 3
	v_bitop3_b32 v2, v0, v2, 7 bitop3:0x78
	v_lshlrev_b32_e32 v187, 4, v2
	v_bitop3_b32 v2, v0, v1, 2 bitop3:0x36
	s_waitcnt vmcnt(2)
	s_barrier
	v_lshlrev_b32_e32 v188, 4, v2
	v_bitop3_b32 v2, v0, v1, 4 bitop3:0x36
	v_bitop3_b32 v0, v0, v1, 6 bitop3:0x36
	v_lshlrev_b32_e32 v190, 4, v0
	v_mov_b32_e32 v0, 0
	v_ashrrev_i32_e32 v123, 31, v122
	s_or_b32 s9, s9, 0x2080
	s_or_b32 s16, s10, 0x80
	v_lshlrev_b32_e32 v189, 4, v2
	s_lshl_b32 s17, s15, 6
	s_mov_b32 s18, 0
	v_mov_b32_e32 v1, v0
	v_mov_b32_e32 v2, v0
	v_mov_b32_e32 v3, v0
	v_mov_b32_e32 v4, v0
	v_mov_b32_e32 v5, v0
	v_mov_b32_e32 v6, v0
	v_mov_b32_e32 v7, v0
	v_mov_b32_e32 v8, v0
	v_mov_b32_e32 v9, v0
	v_mov_b32_e32 v10, v0
	v_mov_b32_e32 v11, v0
	v_mov_b32_e32 v12, v0
	v_mov_b32_e32 v13, v0
	v_mov_b32_e32 v14, v0
	v_mov_b32_e32 v15, v0
	v_mov_b32_e32 v32, v0
	v_mov_b32_e32 v33, v0
	v_mov_b32_e32 v34, v0
	v_mov_b32_e32 v35, v0
	v_mov_b32_e32 v36, v0
	v_mov_b32_e32 v37, v0
	v_mov_b32_e32 v38, v0
	v_mov_b32_e32 v39, v0
	v_mov_b32_e32 v40, v0
	v_mov_b32_e32 v41, v0
	v_mov_b32_e32 v42, v0
	v_mov_b32_e32 v43, v0
	v_mov_b32_e32 v44, v0
	v_mov_b32_e32 v45, v0
	v_mov_b32_e32 v46, v0
	v_mov_b32_e32 v47, v0
	v_mov_b32_e32 v16, v0
	v_mov_b32_e32 v17, v0
	v_mov_b32_e32 v18, v0
	v_mov_b32_e32 v19, v0
	v_mov_b32_e32 v20, v0
	v_mov_b32_e32 v21, v0
	v_mov_b32_e32 v22, v0
	v_mov_b32_e32 v23, v0
	v_mov_b32_e32 v24, v0
	v_mov_b32_e32 v25, v0
	v_mov_b32_e32 v26, v0
	v_mov_b32_e32 v27, v0
	v_mov_b32_e32 v28, v0
	v_mov_b32_e32 v29, v0
	v_mov_b32_e32 v30, v0
	v_mov_b32_e32 v31, v0
	v_mov_b32_e32 v48, v0
	v_mov_b32_e32 v49, v0
	v_mov_b32_e32 v50, v0
	v_mov_b32_e32 v51, v0
	v_mov_b32_e32 v52, v0
	v_mov_b32_e32 v53, v0
	v_mov_b32_e32 v54, v0
	v_mov_b32_e32 v55, v0
	v_mov_b32_e32 v56, v0
	v_mov_b32_e32 v57, v0
	v_mov_b32_e32 v58, v0
	v_mov_b32_e32 v59, v0
	v_mov_b32_e32 v60, v0
	v_mov_b32_e32 v61, v0
	v_mov_b32_e32 v62, v0
	v_mov_b32_e32 v63, v0
	v_mov_b32_e32 v128, v0
	v_mov_b32_e32 v129, v0
	v_add_u32_e32 v200, v186, v187
	v_add_u32_e32 v201, v186, v188
	v_add_u32_e32 v202, v186, v189
	v_add_u32_e32 v203, v186, v190
	v_add3_u32 v204, v184, v160, v185
	v_readfirstlane_b32 s18, v183
	v_readlane_b32 s22, v252, 52
	v_readlane_b32 s23, v252, 53
	v_mov_b32_e32 v130, 0
	v_mov_b32_e32 v131, 0
	s_mov_b64 s[12:13], 0xe00
	v_lshl_add_u64 v[206:207], v[126:127], 1, s[22:23]
	v_lshl_add_u64 v[210:211], v[124:125], 1, s[22:23]
	v_lshl_add_u64 v[206:207], v[206:207], 0, s[12:13]
	s_cmpk_lt_u32 s15, 0x7e
	s_cselect_b32 s12, s16, s9
	s_add_i32 s12, s12, s17
	s_mul_i32 s12, s12, 0x1200
	s_mov_b32 s13, 0
	s_add_i32 s10, s18, 0x8000
	s_mov_b32 m0, s10
	v_lshl_add_u64 v[222:223], v[206:207], 0, s[12:13]
	global_load_lds_dwordx4 v[222:223], off
	s_add_i32 m0, s10, 0x2000
	v_lshl_add_u64 v[222:223], v[210:211], 0, s[12:13]
	global_load_lds_dwordx4 v[222:223], off
	ds_read_b128 v[112:115], v200
	ds_read_b128 v[116:119], v200 offset:4096
	ds_read_b128 v[148:151], v201
	ds_read_b128 v[152:155], v201 offset:4096
	ds_read_b128 v[156:159], v202
	ds_read_b128 v[162:165], v202 offset:4096
	ds_read_b128 v[174:177], v203
	ds_read_b128 v[178:181], v203 offset:4096
	s_waitcnt lgkmcnt(0)
	v_mfma_f32_32x32x16_bf16 v[64:79], v[112:115], v[80:83], 0
	v_mfma_f32_32x32x16_bf16 v[96:111], v[116:119], v[80:83], 0
	v_mfma_f32_32x32x16_bf16 v[64:79], v[148:151], v[84:87], v[64:79]
	v_mfma_f32_32x32x16_bf16 v[96:111], v[152:155], v[84:87], v[96:111]
	v_mfma_f32_32x32x16_bf16 v[132:147], v[156:159], v[88:91], 0
	v_mfma_f32_32x32x16_bf16 v[184:199], v[162:165], v[88:91], 0
	v_mfma_f32_32x32x16_bf16 v[132:147], v[174:177], v[92:95], v[132:147]
	v_mfma_f32_32x32x16_bf16 v[184:199], v[178:181], v[92:95], v[184:199]
	s_nop 7
	v_exp_f32_e32 v64, v64
	v_exp_f32_e32 v65, v65
	v_exp_f32_e32 v66, v66
	v_exp_f32_e32 v67, v67
	v_exp_f32_e32 v68, v68
	v_exp_f32_e32 v69, v69
	v_exp_f32_e32 v70, v70
	v_exp_f32_e32 v71, v71
	v_exp_f32_e32 v72, v72
	v_exp_f32_e32 v73, v73
	v_exp_f32_e32 v74, v74
	v_exp_f32_e32 v75, v75
	v_exp_f32_e32 v76, v76
	v_exp_f32_e32 v77, v77
	v_exp_f32_e32 v78, v78
	v_exp_f32_e32 v79, v79
	v_add_f32_e32 v128, v64, v128
	v_add_f32_e32 v130, v65, v130
	v_add_f32_e32 v128, v66, v128
	v_add_f32_e32 v130, v67, v130
	v_add_f32_e32 v128, v68, v128
	v_add_f32_e32 v130, v69, v130
	v_add_f32_e32 v128, v70, v128
	v_add_f32_e32 v130, v71, v130
	v_add_f32_e32 v128, v72, v128
	v_add_f32_e32 v130, v73, v130
	v_add_f32_e32 v128, v74, v128
	v_add_f32_e32 v130, v75, v130
	v_add_f32_e32 v128, v76, v128
	v_add_f32_e32 v130, v77, v130
	v_add_f32_e32 v128, v78, v128
	v_add_f32_e32 v130, v79, v130
	v_cvt_pk_bf16_f32 v64, v64, v65
	v_cvt_pk_bf16_f32 v65, v66, v67
	v_cvt_pk_bf16_f32 v66, v68, v69
	v_cvt_pk_bf16_f32 v67, v70, v71
	v_cvt_pk_bf16_f32 v68, v72, v73
	v_cvt_pk_bf16_f32 v69, v74, v75
	v_cvt_pk_bf16_f32 v70, v76, v77
	v_cvt_pk_bf16_f32 v71, v78, v79
	v_exp_f32_e32 v96, v96
	v_exp_f32_e32 v97, v97
	v_exp_f32_e32 v98, v98
	v_exp_f32_e32 v99, v99
	v_exp_f32_e32 v100, v100
	v_exp_f32_e32 v101, v101
	v_exp_f32_e32 v102, v102
	v_exp_f32_e32 v103, v103
	v_exp_f32_e32 v104, v104
	v_exp_f32_e32 v105, v105
	v_exp_f32_e32 v106, v106
	v_exp_f32_e32 v107, v107
	v_exp_f32_e32 v108, v108
	v_exp_f32_e32 v109, v109
	v_exp_f32_e32 v110, v110
	v_exp_f32_e32 v111, v111
	v_add_f32_e32 v128, v96, v128
	v_add_f32_e32 v130, v97, v130
	v_add_f32_e32 v128, v98, v128
	v_add_f32_e32 v130, v99, v130
	v_add_f32_e32 v128, v100, v128
	v_add_f32_e32 v130, v101, v130
	v_add_f32_e32 v128, v102, v128
	v_add_f32_e32 v130, v103, v130
	v_add_f32_e32 v128, v104, v128
	v_add_f32_e32 v130, v105, v130
	v_add_f32_e32 v128, v106, v128
	v_add_f32_e32 v130, v107, v130
	v_add_f32_e32 v128, v108, v128
	v_add_f32_e32 v130, v109, v130
	v_add_f32_e32 v128, v110, v128
	v_add_f32_e32 v130, v111, v130
	v_cvt_pk_bf16_f32 v96, v96, v97
	v_cvt_pk_bf16_f32 v97, v98, v99
	v_cvt_pk_bf16_f32 v98, v100, v101
	v_cvt_pk_bf16_f32 v99, v102, v103
	v_cvt_pk_bf16_f32 v100, v104, v105
	v_cvt_pk_bf16_f32 v101, v106, v107
	v_cvt_pk_bf16_f32 v102, v108, v109
	v_cvt_pk_bf16_f32 v103, v110, v111
	s_waitcnt vmcnt(2)
	s_barrier
	v_readlane_b32 s10, v251, 44
	s_cmpk_lt_u32 s10, 0x100
	s_cbranch_scc1 .Ldiff_noprio
	s_setprio 1
